# P1 row sums: xor-1 and xor-2 butterfly steps by DPP quad_perm (remaining steps unchanged)
# baseline (speedup 1.0000x reference)
.LBB0_184:
	s_or_b64 exec, exec, s[4:5]
	s_lshl_b32 s0, s3, 6
	s_lshl_b32 s1, s62, 3
	s_add_i32 s6, s0, s1
	s_ashr_i32 s0, s6, 8
	s_ashr_i32 s1, s0, 31
	s_lshl_b64 s[0:1], s[0:1], 19
	s_add_u32 s5, s52, s0
	s_addc_u32 s4, s53, s1
	s_ashr_i32 s7, s6, 31
	s_lshl_b64 s[0:1], s[6:7], 12
	s_add_u32 s0, s36, s0
	v_ashrrev_i32_e32 v21, 31, v20
	s_addc_u32 s1, s37, s1
	v_lshlrev_b64 v[88:89], 4, v[20:21]
	v_lshl_add_u64 v[0:1], s[0:1], 0, v[88:89]
	s_waitcnt lgkmcnt(0)
	s_barrier
	global_load_dwordx4 v[8:11], v[0:1], off nt
	global_load_dwordx4 v[16:19], v[0:1], off offset:1024 nt
	global_load_dwordx4 v[32:35], v[0:1], off offset:3072 nt
	global_load_dwordx4 v[24:27], v[0:1], off offset:2048 nt
	v_mbcnt_lo_u32_b32 v0, -1, 0
	s_or_b32 s0, s6, 1
	v_mbcnt_hi_u32_b32 v2, -1, v0
	s_ashr_i32 s1, s0, 31
	v_and_b32_e32 v0, 64, v2
	s_lshl_b64 s[0:1], s[0:1], 12
	v_xor_b32_e32 v1, 1, v2
	v_add_u32_e32 v12, 64, v0
	s_add_u32 s0, s36, s0
	v_cmp_lt_i32_e32 vcc, v1, v12
	s_addc_u32 s1, s37, s1
	v_xor_b32_e32 v3, 2, v2
	v_cndmask_b32_e32 v13, v2, v1, vcc
	v_lshl_add_u64 v[0:1], s[0:1], 0, v[88:89]
	global_load_dwordx4 v[52:55], v[0:1], off nt
	global_load_dwordx4 v[40:43], v[0:1], off offset:1024 nt
	global_load_dwordx4 v[48:51], v[0:1], off offset:2048 nt
	global_load_dwordx4 v[36:39], v[0:1], off offset:3072 nt
	v_xor_b32_e32 v4, 4, v2
	v_cmp_lt_i32_e32 vcc, v3, v12
	v_xor_b32_e32 v5, 8, v2
	v_xor_b32_e32 v6, 16, v2
	v_cndmask_b32_e32 v3, v2, v3, vcc
	v_cmp_lt_i32_e32 vcc, v4, v12
	v_xor_b32_e32 v7, 32, v2
	v_lshlrev_b32_e32 v109, 2, v3
	v_cndmask_b32_e32 v4, v2, v4, vcc
	v_cmp_lt_i32_e32 vcc, v5, v12
	v_lshlrev_b32_e32 v108, 2, v4
	v_lshlrev_b32_e32 v110, 2, v13
	v_cndmask_b32_e32 v5, v2, v5, vcc
	v_cmp_lt_i32_e32 vcc, v6, v12
	v_lshlrev_b32_e32 v107, 2, v5
	s_or_b32 s0, s6, 2
	v_cndmask_b32_e32 v6, v2, v6, vcc
	v_cmp_lt_i32_e32 vcc, v7, v12
	v_lshlrev_b32_e32 v106, 2, v6
	s_ashr_i32 s1, s0, 31
	v_cndmask_b32_e32 v2, v2, v7, vcc
	v_lshlrev_b32_e32 v105, 2, v2
	s_lshl_b64 s[0:1], s[0:1], 12
	s_add_u32 s0, s36, s0
	s_addc_u32 s1, s37, s1
	v_mov_b32_e32 v104, 0x358637bd
	s_mov_b32 s3, 0xf800000
	s_or_b32 s8, s6, 3
	s_ashr_i32 s9, s8, 31
	v_mov_b32_e32 v111, 0x260
	v_lshl_add_u32 v30, v20, 4, 0
	v_lshlrev_b32_e32 v85, 8, v20
	v_and_b32_e32 v84, 15, v20
	s_waitcnt vmcnt(7)
	v_pk_mul_f32 v[0:1], v[10:11], v[10:11]
	v_pk_mul_f32 v[2:3], v[8:9], v[8:9]
	s_waitcnt vmcnt(6)
	v_pk_mul_f32 v[4:5], v[18:19], v[18:19]
	v_pk_mul_f32 v[6:7], v[16:17], v[16:17]
	v_pk_mov_b32 v[22:23], v[2:3], v[0:1] op_sel:[1,0]
	v_mov_b32_e32 v3, v1
	v_pk_mov_b32 v[0:1], v[6:7], v[4:5] op_sel:[1,0]
	v_mov_b32_e32 v7, v5
	s_waitcnt vmcnt(5)
	v_mul_f32_e32 v15, v32, v32
	s_waitcnt vmcnt(4)
	v_mul_f32_e32 v12, v25, v25
	v_mul_f32_e32 v14, v27, v27
	v_pk_add_f32 v[2:3], v[22:23], v[2:3]
	v_pk_add_f32 v[0:1], v[0:1], v[6:7]
	v_mul_f32_e32 v21, v33, v33
	v_mul_f32_e32 v28, v34, v34
	v_mul_f32_e32 v29, v35, v35
	v_pk_fma_f32 v[4:5], v[24:25], v[24:25], v[12:13] op_sel_hi:[1,1,0]
	v_pk_fma_f32 v[12:13], v[26:27], v[26:27], v[14:15] op_sel_hi:[1,1,0]
	v_pk_add_f32 v[2:3], v[2:3], v[2:3] op_sel:[0,1] op_sel_hi:[1,0]
	v_pk_add_f32 v[0:1], v[0:1], v[0:1] op_sel:[0,1] op_sel_hi:[1,0]
	v_mov_b32_e32 v5, v28
	v_mov_b32_e32 v13, v29
	v_mov_b32_e32 v3, v15
	v_mov_b32_e32 v1, v21
	v_pk_add_f32 v[4:5], v[4:5], v[12:13]
	v_pk_add_f32 v[0:1], v[2:3], v[0:1]
	s_nop 0
	v_pk_add_f32 v[0:1], v[0:1], v[4:5]
	s_waitcnt vmcnt(3)
	v_pk_mul_f32 v[4:5], v[52:53], v[52:53]
	v_add_f32_e32 v2, v0, v1
	v_lshl_add_u64 v[0:1], s[0:1], 0, v[88:89]
	global_load_dwordx4 v[64:67], v[0:1], off nt
	global_load_dwordx4 v[60:63], v[0:1], off offset:1024 nt
	global_load_dwordx4 v[56:59], v[0:1], off offset:2048 nt
	global_load_dwordx4 v[44:47], v[0:1], off offset:3072 nt
	s_lshl_b64 s[0:1], s[8:9], 12
	s_waitcnt lgkmcnt(0)
	s_nop 4
	v_add_f32_dpp v2, v2, v2 quad_perm:[1,0,3,2] row_mask:0xf bank_mask:0xf
	s_add_u32 s0, s36, s0
	s_addc_u32 s1, s37, s1
	s_lshl_b32 s7, s6, 7
	v_lshl_add_u64 v[0:1], s[0:1], 0, v[88:89]
	s_waitcnt lgkmcnt(0)
	s_nop 4
	v_add_f32_dpp v2, v2, v2 quad_perm:[2,3,0,1] row_mask:0xf bank_mask:0xf
	ds_bpermute_b32 v3, v108, v2
	s_and_b32 s7, s7, 0x7c00
	global_load_dwordx4 v[76:79], v[0:1], off nt
	global_load_dwordx4 v[68:71], v[0:1], off offset:1024 nt
	s_add_u32 s10, s5, s7
	s_addc_u32 s11, s4, 0
	s_waitcnt lgkmcnt(0)
	v_add_f32_e32 v2, v2, v3
	ds_bpermute_b32 v3, v107, v2
	s_or_b32 s0, s6, 4
	s_ashr_i32 s1, s0, 31
	s_lshl_b64 s[0:1], s[0:1], 12
	global_load_dwordx4 v[80:83], v[0:1], off offset:2048 nt
	global_load_dwordx4 v[72:75], v[0:1], off offset:3072 nt
	s_waitcnt lgkmcnt(0)
	v_add_f32_e32 v6, v2, v3
	ds_bpermute_b32 v7, v106, v6
	v_pk_mul_f32 v[2:3], v[54:55], v[54:55]
	s_add_u32 s8, s36, s0
	v_pk_mov_b32 v[12:13], v[4:5], v[2:3] op_sel:[1,0]
	v_mov_b32_e32 v5, v3
	s_waitcnt lgkmcnt(0)
	v_add_f32_e32 v14, v6, v7
	ds_bpermute_b32 v15, v105, v14
	v_pk_add_f32 v[2:3], v[12:13], v[4:5]
	s_waitcnt vmcnt(10)
	v_pk_mul_f32 v[6:7], v[42:43], v[42:43]
	v_pk_add_f32 v[2:3], v[2:3], v[2:3] op_sel:[0,1] op_sel_hi:[1,0]
	s_addc_u32 s9, s37, s1
	s_waitcnt lgkmcnt(0)
	v_add_f32_e32 v4, v14, v15
	v_fmamk_f32 v4, v4, 0x3a800000, v104
	v_mul_f32_e32 v5, 0x4f800000, v4
	v_cmp_gt_f32_e32 vcc, s3, v4
	s_nop 1
	v_cndmask_b32_e32 v14, v4, v5, vcc
	v_pk_mul_f32 v[4:5], v[40:41], v[40:41]
	v_sqrt_f32_e32 v15, v14
	v_pk_mov_b32 v[12:13], v[4:5], v[6:7] op_sel:[1,0]
	v_mov_b32_e32 v5, v7
	v_pk_add_f32 v[4:5], v[12:13], v[4:5]
	s_waitcnt vmcnt(8)
	v_mul_f32_e32 v6, v36, v36
	v_mul_f32_e32 v7, v37, v37
	v_pk_add_f32 v[4:5], v[4:5], v[4:5] op_sel:[0,1] op_sel_hi:[1,0]
	v_mov_b32_e32 v3, v6
	v_mov_b32_e32 v5, v7
	v_pk_add_f32 v[2:3], v[2:3], v[4:5]
	v_mul_f32_e32 v4, v49, v49
	v_mul_f32_e32 v6, v51, v51
	v_mul_f32_e32 v12, v38, v38
	v_mul_f32_e32 v13, v39, v39
	v_pk_fma_f32 v[4:5], v[48:49], v[48:49], v[4:5] op_sel_hi:[1,1,0]
	v_pk_fma_f32 v[6:7], v[50:51], v[50:51], v[6:7] op_sel_hi:[1,1,0]
	v_mov_b32_e32 v5, v12
	v_mov_b32_e32 v7, v13
	v_pk_add_f32 v[4:5], v[4:5], v[6:7]
	s_nop 0
	v_pk_add_f32 v[2:3], v[2:3], v[4:5]
	v_add_u32_e32 v4, -1, v15
	v_add_f32_e32 v2, v2, v3
	v_fma_f32 v5, -v4, v15, v14
	v_cmp_ge_f32_e64 s[0:1], 0, v5
	v_add_u32_e32 v5, 1, v15
	v_fma_f32 v6, -v5, v15, v14
	s_waitcnt lgkmcnt(0)
	s_nop 4
	v_add_f32_dpp v2, v2, v2 quad_perm:[1,0,3,2] row_mask:0xf bank_mask:0xf
	v_cndmask_b32_e64 v4, v15, v4, s[0:1]
	v_cmp_lt_f32_e64 s[0:1], 0, v6
	s_waitcnt lgkmcnt(0)
	s_nop 4
	v_add_f32_dpp v2, v2, v2 quad_perm:[2,3,0,1] row_mask:0xf bank_mask:0xf
	ds_bpermute_b32 v3, v108, v2
	v_cndmask_b32_e64 v4, v4, v5, s[0:1]
	v_mul_f32_e32 v5, 0x37800000, v4
	v_cndmask_b32_e32 v4, v4, v5, vcc
	v_cmp_class_f32_e32 vcc, v14, v111
	s_waitcnt lgkmcnt(0)
	v_add_f32_e32 v2, v2, v3
	ds_bpermute_b32 v3, v107, v2
	v_cndmask_b32_e32 v12, v4, v14, vcc
	v_div_scale_f32 v13, s[0:1], v12, v12, 1.0
	v_rcp_f32_e32 v14, v13
	s_waitcnt lgkmcnt(0)
	v_add_f32_e32 v2, v2, v3
	ds_bpermute_b32 v3, v106, v2
	v_div_scale_f32 v15, vcc, 1.0, v12, 1.0
	v_fma_f32 v0, -v13, v14, 1.0
	v_fmac_f32_e32 v14, v0, v14
	s_waitcnt lgkmcnt(0)
	v_add_f32_e32 v0, v2, v3
	ds_bpermute_b32 v1, v105, v0
	s_waitcnt vmcnt(7)
	v_pk_mul_f32 v[2:3], v[64:65], v[64:65]
	v_mul_f32_e32 v21, v15, v14
	v_fma_f32 v22, -v13, v21, v15
	v_fmac_f32_e32 v21, v22, v14
	s_waitcnt lgkmcnt(0)
	v_add_f32_e32 v0, v0, v1
	v_fmamk_f32 v0, v0, 0x3a800000, v104
	v_mul_f32_e32 v1, 0x4f800000, v0
	v_cmp_gt_f32_e64 s[0:1], s3, v0
	s_nop 1
	v_cndmask_b32_e64 v23, v0, v1, s[0:1]
	v_pk_mul_f32 v[0:1], v[66:67], v[66:67]
	v_sqrt_f32_e32 v28, v23
	v_pk_mov_b32 v[4:5], v[2:3], v[0:1] op_sel:[1,0]
	v_mov_b32_e32 v3, v1
	v_pk_add_f32 v[0:1], v[4:5], v[2:3]
	s_waitcnt vmcnt(6)
	v_pk_mul_f32 v[2:3], v[62:63], v[62:63]
	v_pk_mul_f32 v[4:5], v[60:61], v[60:61]
	v_pk_add_f32 v[0:1], v[0:1], v[0:1] op_sel:[0,1] op_sel_hi:[1,0]
	v_pk_mov_b32 v[6:7], v[4:5], v[2:3] op_sel:[1,0]
	v_mov_b32_e32 v5, v3
	v_pk_add_f32 v[2:3], v[6:7], v[4:5]
	s_waitcnt vmcnt(4)
	v_mul_f32_e32 v4, v44, v44
	v_mul_f32_e32 v5, v45, v45
	v_pk_add_f32 v[2:3], v[2:3], v[2:3] op_sel:[0,1] op_sel_hi:[1,0]
	v_mov_b32_e32 v1, v4
	v_mov_b32_e32 v3, v5
	v_pk_add_f32 v[0:1], v[0:1], v[2:3]
	v_mul_f32_e32 v2, v57, v57
	v_mul_f32_e32 v4, v59, v59
	v_mul_f32_e32 v6, v46, v46
	v_mul_f32_e32 v7, v47, v47
	v_pk_fma_f32 v[2:3], v[56:57], v[56:57], v[2:3] op_sel_hi:[1,1,0]
	v_pk_fma_f32 v[4:5], v[58:59], v[58:59], v[4:5] op_sel_hi:[1,1,0]
	v_mov_b32_e32 v3, v6
	v_mov_b32_e32 v5, v7
	v_pk_add_f32 v[2:3], v[2:3], v[4:5]
	s_nop 0
	v_pk_add_f32 v[0:1], v[0:1], v[2:3]
	v_add_u32_e32 v3, -1, v28
	v_add_f32_e32 v0, v0, v1
	v_fma_f32 v4, -v3, v28, v23
	v_cmp_ge_f32_e64 s[4:5], 0, v4
	v_add_u32_e32 v4, 1, v28
	v_fma_f32 v5, -v4, v28, v23
	s_waitcnt lgkmcnt(0)
	s_nop 4
	v_add_f32_dpp v0, v0, v0 quad_perm:[1,0,3,2] row_mask:0xf bank_mask:0xf
	v_cndmask_b32_e64 v3, v28, v3, s[4:5]
	v_cmp_lt_f32_e64 s[4:5], 0, v5
	v_fma_f32 v2, -v13, v21, v15
	v_div_fmas_f32 v2, v2, v14, v21
	s_waitcnt lgkmcnt(0)
	s_nop 4
	v_add_f32_dpp v0, v0, v0 quad_perm:[2,3,0,1] row_mask:0xf bank_mask:0xf
	ds_bpermute_b32 v1, v108, v0
	v_cndmask_b32_e64 v3, v3, v4, s[4:5]
	v_mul_f32_e32 v4, 0x37800000, v3
	v_cndmask_b32_e64 v3, v3, v4, s[0:1]
	v_cmp_class_f32_e64 s[0:1], v23, v111
	s_waitcnt lgkmcnt(0)
	v_add_f32_e32 v0, v0, v1
	ds_bpermute_b32 v1, v107, v0
	v_cndmask_b32_e64 v13, v3, v23, s[0:1]
	v_div_scale_f32 v15, s[0:1], v13, v13, 1.0
	v_rcp_f32_e32 v22, v15
	s_waitcnt lgkmcnt(0)
	v_add_f32_e32 v0, v0, v1
	ds_bpermute_b32 v1, v106, v0
	v_div_fixup_f32 v86, v2, v12, 1.0
	v_fma_f32 v2, -v15, v22, 1.0
	v_fmac_f32_e32 v22, v2, v22
	s_waitcnt vmcnt(3)
	v_pk_mul_f32 v[2:3], v[76:77], v[76:77]
	s_waitcnt lgkmcnt(0)
	v_add_f32_e32 v0, v0, v1
	ds_bpermute_b32 v1, v105, v0
	v_div_scale_f32 v12, vcc, 1.0, v13, 1.0
	v_mul_f32_e32 v14, v12, v22
	v_fma_f32 v21, -v15, v14, v12
	s_waitcnt lgkmcnt(0)
	v_add_f32_e32 v0, v0, v1
	v_fmamk_f32 v0, v0, 0x3a800000, v104
	v_mul_f32_e32 v1, 0x4f800000, v0
	v_cmp_gt_f32_e64 s[0:1], s3, v0
	v_fmac_f32_e32 v14, v21, v22
	v_pk_mul_f32 v[16:17], v[16:17], v[86:87] op_sel_hi:[1,0]
	v_cndmask_b32_e64 v23, v0, v1, s[0:1]
	v_pk_mul_f32 v[0:1], v[78:79], v[78:79]
	v_sqrt_f32_e32 v28, v23
	v_pk_mov_b32 v[4:5], v[2:3], v[0:1] op_sel:[1,0]
	v_mov_b32_e32 v3, v1
	v_pk_add_f32 v[0:1], v[4:5], v[2:3]
	s_waitcnt vmcnt(2)
	v_pk_mul_f32 v[2:3], v[70:71], v[70:71]
	v_pk_mul_f32 v[4:5], v[68:69], v[68:69]
	v_pk_add_f32 v[0:1], v[0:1], v[0:1] op_sel:[0,1] op_sel_hi:[1,0]
	v_pk_mov_b32 v[6:7], v[4:5], v[2:3] op_sel:[1,0]
	v_mov_b32_e32 v5, v3
	v_pk_add_f32 v[2:3], v[6:7], v[4:5]
	s_waitcnt vmcnt(0)
	v_mul_f32_e32 v4, v72, v72
	v_mul_f32_e32 v5, v73, v73
	v_pk_add_f32 v[2:3], v[2:3], v[2:3] op_sel:[0,1] op_sel_hi:[1,0]
	v_mov_b32_e32 v1, v4
	v_mov_b32_e32 v3, v5
	v_pk_add_f32 v[0:1], v[0:1], v[2:3]
	v_mul_f32_e32 v2, v81, v81
	v_mul_f32_e32 v4, v83, v83
	v_mul_f32_e32 v6, v74, v74
	v_mul_f32_e32 v7, v75, v75
	v_pk_fma_f32 v[2:3], v[80:81], v[80:81], v[2:3] op_sel_hi:[1,1,0]
	v_pk_fma_f32 v[4:5], v[82:83], v[82:83], v[4:5] op_sel_hi:[1,1,0]
	v_mov_b32_e32 v3, v6
	v_mov_b32_e32 v5, v7
	v_pk_add_f32 v[2:3], v[2:3], v[4:5]
	v_pk_mul_f32 v[18:19], v[18:19], v[86:87] op_sel_hi:[1,0]
	v_pk_add_f32 v[0:1], v[0:1], v[2:3]
	v_add_u32_e32 v3, -1, v28
	v_add_f32_e32 v0, v0, v1
	v_fma_f32 v4, -v3, v28, v23
	v_cmp_ge_f32_e64 s[4:5], 0, v4
	v_add_u32_e32 v4, 1, v28
	v_fma_f32 v5, -v4, v28, v23
	s_waitcnt lgkmcnt(0)
	s_nop 4
	v_add_f32_dpp v0, v0, v0 quad_perm:[1,0,3,2] row_mask:0xf bank_mask:0xf
	v_cndmask_b32_e64 v3, v28, v3, s[4:5]
	v_cmp_lt_f32_e64 s[4:5], 0, v5
	v_fma_f32 v2, -v15, v14, v12
	v_div_fmas_f32 v2, v2, v22, v14
	s_waitcnt lgkmcnt(0)
	s_nop 4
	v_add_f32_dpp v0, v0, v0 quad_perm:[2,3,0,1] row_mask:0xf bank_mask:0xf
	ds_bpermute_b32 v1, v108, v0
	v_cndmask_b32_e64 v3, v3, v4, s[4:5]
	v_mul_f32_e32 v4, 0x37800000, v3
	v_cndmask_b32_e64 v3, v3, v4, s[0:1]
	v_cmp_class_f32_e64 s[0:1], v23, v111
	s_waitcnt lgkmcnt(0)
	v_add_f32_e32 v0, v0, v1
	ds_bpermute_b32 v1, v107, v0
	v_cndmask_b32_e64 v3, v3, v23, s[0:1]
	v_div_scale_f32 v4, s[0:1], v3, v3, 1.0
	v_rcp_f32_e32 v5, v4
	s_waitcnt lgkmcnt(0)
	v_add_f32_e32 v0, v0, v1
	ds_bpermute_b32 v1, v106, v0
	v_div_fixup_f32 v90, v2, v13, 1.0
	v_fma_f32 v2, -v4, v5, 1.0
	v_fmac_f32_e32 v5, v2, v5
	v_div_scale_f32 v2, vcc, 1.0, v3, 1.0
	s_waitcnt lgkmcnt(0)
	v_add_f32_e32 v0, v0, v1
	ds_bpermute_b32 v1, v105, v0
	v_mul_f32_e32 v6, v2, v5
	v_fma_f32 v7, -v4, v6, v2
	v_fmac_f32_e32 v6, v7, v5
	v_fma_f32 v2, -v4, v6, v2
	s_waitcnt lgkmcnt(0)
	v_add_f32_e32 v0, v0, v1
	v_fmamk_f32 v0, v0, 0x3a800000, v104
	v_mul_f32_e32 v1, 0x4f800000, v0
	v_cmp_gt_f32_e64 s[0:1], s3, v0
	v_div_fmas_f32 v2, v2, v5, v6
	v_div_fixup_f32 v92, v2, v3, 1.0
	v_cndmask_b32_e64 v0, v0, v1, s[0:1]
	v_sqrt_f32_e32 v1, v0
	v_pk_mul_f32 v[22:23], v[8:9], v[86:87] op_sel_hi:[1,0]
	v_pk_mul_f32 v[28:29], v[10:11], v[86:87] op_sel_hi:[1,0]
	v_pk_mul_f32 v[100:101], v[24:25], v[86:87] op_sel_hi:[1,0]
	v_add_u32_e32 v4, -1, v1
	v_fma_f32 v7, -v4, v1, v0
	v_cmp_ge_f32_e64 s[4:5], 0, v7
	v_add_u32_e32 v7, 1, v1
	v_pk_mul_f32 v[102:103], v[26:27], v[86:87] op_sel_hi:[1,0]
	v_cndmask_b32_e64 v4, v1, v4, s[4:5]
	v_fma_f32 v1, -v7, v1, v0
	v_cmp_lt_f32_e64 s[4:5], 0, v1
	v_add_u32_e32 v87, 0x8000, v85
	v_pk_mul_f32 v[32:33], v[32:33], v[86:87] op_sel_hi:[1,0]
	v_cndmask_b32_e64 v1, v4, v7, s[4:5]
	v_mul_f32_e32 v4, 0x37800000, v1
	v_cndmask_b32_e64 v1, v1, v4, s[0:1]
	v_cmp_class_f32_e64 s[0:1], v0, v111
	v_pk_mul_f32 v[34:35], v[34:35], v[86:87] op_sel_hi:[1,0]
	s_nop 0
	v_cndmask_b32_e64 v0, v1, v0, s[0:1]
	v_div_scale_f32 v1, s[0:1], v0, v0, 1.0
	v_rcp_f32_e32 v4, v1
	s_movk_i32 s0, 0xf000
	v_and_or_b32 v20, v85, s0, v84
	v_ashrrev_i32_e32 v21, 31, v20
	v_fma_f32 v2, -v1, v4, 1.0
	v_fmac_f32_e32 v4, v2, v4
	v_div_scale_f32 v2, vcc, 1.0, v0, 1.0
	v_mul_f32_e32 v3, v2, v4
	v_fma_f32 v5, -v1, v3, v2
	v_fmac_f32_e32 v3, v5, v4
	v_fma_f32 v1, -v1, v3, v2
	v_div_fmas_f32 v1, v1, v4, v3
	v_div_fixup_f32 v94, v1, v0, 1.0
	ds_read_b128 v[0:3], v30
	ds_read_b128 v[4:7], v30 offset:4096
	ds_read_b128 v[8:11], v30 offset:1024
	ds_read_b128 v[12:15], v30 offset:5120
	v_lshl_add_u64 v[96:97], v[20:21], 3, s[10:11]
	s_waitcnt lgkmcnt(0)
	v_pk_fma_f32 v[28:29], v[28:29], v[2:3], v[6:7]
	s_waitcnt lgkmcnt(0)
	v_pk_fma_f32 v[18:19], v[18:19], v[10:11], v[14:15]
	v_pk_fma_f32 v[16:17], v[16:17], v[8:9], v[12:13]
	v_pk_fma_f32 v[22:23], v[22:23], v[0:1], v[4:5]
	v_cvt_pk_bf16_f32 v16, v16, v17
	v_cvt_pk_bf16_f32 v17, v18, v19
	v_add_u32_e32 v18, 0x4000, v85
	v_and_or_b32 v18, v18, s0, v84
	v_ashrrev_i32_e32 v19, 31, v18
	v_cvt_pk_bf16_f32 v22, v22, v23
	v_cvt_pk_bf16_f32 v23, v28, v29
	v_lshl_add_u64 v[98:99], v[18:19], 3, s[10:11]
	global_store_dwordx2 v[96:97], v[22:23], off
	global_store_dwordx2 v[98:99], v[16:17], off
	ds_read_b128 v[16:19], v30 offset:2048
	ds_read_b128 v[20:23], v30 offset:6144
	ds_read_b128 v[24:27], v30 offset:3072
	ds_read_b128 v[28:31], v30 offset:7168
	s_waitcnt lgkmcnt(0)
	v_pk_fma_f32 v[100:101], v[100:101], v[16:17], v[20:21]
	s_waitcnt lgkmcnt(0)
	v_pk_fma_f32 v[34:35], v[34:35], v[26:27], v[30:31]
	v_pk_fma_f32 v[32:33], v[32:33], v[24:25], v[28:29]
	v_cvt_pk_bf16_f32 v112, v100, v101
	v_cvt_pk_bf16_f32 v32, v32, v33
	v_cvt_pk_bf16_f32 v33, v34, v35
	v_add_u32_e32 v34, 0xc000, v85
	v_and_or_b32 v100, v87, s0, v84
	v_and_or_b32 v34, v34, s0, v84
	v_pk_fma_f32 v[102:103], v[102:103], v[18:19], v[22:23]
	v_ashrrev_i32_e32 v101, 31, v100
	v_ashrrev_i32_e32 v35, 31, v34
	v_cvt_pk_bf16_f32 v113, v102, v103
	v_lshl_add_u64 v[100:101], v[100:101], 3, s[10:11]
	v_lshl_add_u64 v[102:103], v[34:35], 3, s[10:11]
	global_store_dwordx2 v[100:101], v[112:113], off
	global_store_dwordx2 v[102:103], v[32:33], off
	v_pk_mul_f32 v[32:33], v[52:53], v[90:91] op_sel_hi:[1,0]
	v_pk_mul_f32 v[34:35], v[54:55], v[90:91] op_sel_hi:[1,0]
	v_pk_fma_f32 v[32:33], v[32:33], v[0:1], v[4:5]
	v_pk_fma_f32 v[34:35], v[34:35], v[2:3], v[6:7]
	v_cvt_pk_bf16_f32 v32, v32, v33
	v_cvt_pk_bf16_f32 v33, v34, v35
	global_store_dwordx2 v[96:97], v[32:33], off offset:128
	v_pk_mul_f32 v[32:33], v[40:41], v[90:91] op_sel_hi:[1,0]
	v_pk_mul_f32 v[34:35], v[42:43], v[90:91] op_sel_hi:[1,0]
	v_pk_fma_f32 v[32:33], v[32:33], v[8:9], v[12:13]
	v_pk_fma_f32 v[34:35], v[34:35], v[10:11], v[14:15]
	v_cvt_pk_bf16_f32 v32, v32, v33
	v_cvt_pk_bf16_f32 v33, v34, v35
	global_store_dwordx2 v[98:99], v[32:33], off offset:128
	v_pk_mul_f32 v[32:33], v[48:49], v[90:91] op_sel_hi:[1,0]
	v_pk_mul_f32 v[34:35], v[50:51], v[90:91] op_sel_hi:[1,0]
	v_pk_fma_f32 v[32:33], v[32:33], v[16:17], v[20:21]
	v_pk_fma_f32 v[34:35], v[34:35], v[18:19], v[22:23]
	v_cvt_pk_bf16_f32 v32, v32, v33
	v_cvt_pk_bf16_f32 v33, v34, v35
	global_store_dwordx2 v[100:101], v[32:33], off offset:128
	v_pk_mul_f32 v[32:33], v[36:37], v[90:91] op_sel_hi:[1,0]
	v_pk_mul_f32 v[34:35], v[38:39], v[90:91] op_sel_hi:[1,0]
	v_pk_fma_f32 v[32:33], v[32:33], v[24:25], v[28:29]
	v_pk_fma_f32 v[34:35], v[34:35], v[26:27], v[30:31]
	v_cvt_pk_bf16_f32 v32, v32, v33
	v_cvt_pk_bf16_f32 v33, v34, v35
	global_store_dwordx2 v[102:103], v[32:33], off offset:128
	v_pk_mul_f32 v[32:33], v[64:65], v[92:93] op_sel_hi:[1,0]
	v_pk_mul_f32 v[34:35], v[66:67], v[92:93] op_sel_hi:[1,0]
	v_pk_fma_f32 v[32:33], v[0:1], v[32:33], v[4:5]
	v_pk_fma_f32 v[34:35], v[2:3], v[34:35], v[6:7]
	v_cvt_pk_bf16_f32 v32, v32, v33
	v_cvt_pk_bf16_f32 v33, v34, v35
	global_store_dwordx2 v[96:97], v[32:33], off offset:256
	v_pk_mul_f32 v[32:33], v[60:61], v[92:93] op_sel_hi:[1,0]
	v_pk_mul_f32 v[34:35], v[62:63], v[92:93] op_sel_hi:[1,0]
	v_pk_fma_f32 v[32:33], v[32:33], v[8:9], v[12:13]
	v_pk_fma_f32 v[34:35], v[34:35], v[10:11], v[14:15]
	v_cvt_pk_bf16_f32 v32, v32, v33
	v_cvt_pk_bf16_f32 v33, v34, v35
	global_store_dwordx2 v[98:99], v[32:33], off offset:256
	v_pk_mul_f32 v[32:33], v[56:57], v[92:93] op_sel_hi:[1,0]
	v_pk_mul_f32 v[34:35], v[58:59], v[92:93] op_sel_hi:[1,0]
	v_pk_fma_f32 v[32:33], v[32:33], v[16:17], v[20:21]
	v_pk_fma_f32 v[34:35], v[34:35], v[18:19], v[22:23]
	v_cvt_pk_bf16_f32 v32, v32, v33
	v_cvt_pk_bf16_f32 v33, v34, v35
	global_store_dwordx2 v[100:101], v[32:33], off offset:256
	v_pk_mul_f32 v[32:33], v[44:45], v[92:93] op_sel_hi:[1,0]
	v_pk_mul_f32 v[34:35], v[46:47], v[92:93] op_sel_hi:[1,0]
	v_pk_fma_f32 v[32:33], v[32:33], v[24:25], v[28:29]
	v_pk_fma_f32 v[34:35], v[34:35], v[26:27], v[30:31]
	v_cvt_pk_bf16_f32 v32, v32, v33
	v_cvt_pk_bf16_f32 v33, v34, v35
	global_store_dwordx2 v[102:103], v[32:33], off offset:256
	v_pk_mul_f32 v[32:33], v[76:77], v[94:95] op_sel_hi:[1,0]
	v_pk_mul_f32 v[34:35], v[78:79], v[94:95] op_sel_hi:[1,0]
	v_pk_fma_f32 v[32:33], v[0:1], v[32:33], v[4:5]
	v_pk_fma_f32 v[34:35], v[2:3], v[34:35], v[6:7]
	v_cvt_pk_bf16_f32 v32, v32, v33
	v_cvt_pk_bf16_f32 v33, v34, v35
	global_store_dwordx2 v[96:97], v[32:33], off offset:384
	v_pk_mul_f32 v[32:33], v[68:69], v[94:95] op_sel_hi:[1,0]
	v_pk_mul_f32 v[34:35], v[70:71], v[94:95] op_sel_hi:[1,0]
	v_pk_fma_f32 v[32:33], v[8:9], v[32:33], v[12:13]
	v_pk_fma_f32 v[34:35], v[10:11], v[34:35], v[14:15]
	v_cvt_pk_bf16_f32 v32, v32, v33
	v_cvt_pk_bf16_f32 v33, v34, v35
	global_store_dwordx2 v[98:99], v[32:33], off offset:384
	v_pk_mul_f32 v[32:33], v[80:81], v[94:95] op_sel_hi:[1,0]
	v_pk_mul_f32 v[34:35], v[82:83], v[94:95] op_sel_hi:[1,0]
	v_pk_fma_f32 v[32:33], v[16:17], v[32:33], v[20:21]
	v_pk_fma_f32 v[34:35], v[18:19], v[34:35], v[22:23]
	v_cvt_pk_bf16_f32 v32, v32, v33
	v_cvt_pk_bf16_f32 v33, v34, v35
	global_store_dwordx2 v[100:101], v[32:33], off offset:384
	v_pk_mul_f32 v[32:33], v[72:73], v[94:95] op_sel_hi:[1,0]
	v_pk_mul_f32 v[34:35], v[74:75], v[94:95] op_sel_hi:[1,0]
	v_pk_fma_f32 v[32:33], v[32:33], v[24:25], v[28:29]
	v_pk_fma_f32 v[34:35], v[34:35], v[26:27], v[30:31]
	v_cvt_pk_bf16_f32 v32, v32, v33
	v_cvt_pk_bf16_f32 v33, v34, v35
	global_store_dwordx2 v[102:103], v[32:33], off offset:384
	v_lshl_add_u64 v[32:33], s[8:9], 0, v[88:89]
	global_load_dwordx4 v[76:79], v[32:33], off nt
	global_load_dwordx4 v[68:71], v[32:33], off offset:1024 nt
	global_load_dwordx4 v[52:55], v[32:33], off offset:3072 nt
	global_load_dwordx4 v[60:63], v[32:33], off offset:2048 nt
	s_or_b32 s0, s6, 5
	s_ashr_i32 s1, s0, 31
	s_lshl_b64 s[0:1], s[0:1], 12
	s_add_u32 s0, s36, s0
	s_addc_u32 s1, s37, s1
	v_lshl_add_u64 v[44:45], s[0:1], 0, v[88:89]
	global_load_dwordx4 v[48:51], v[44:45], off nt
	global_load_dwordx4 v[40:43], v[44:45], off offset:1024 nt
	global_load_dwordx4 v[36:39], v[44:45], off offset:2048 nt
	global_load_dwordx4 v[32:35], v[44:45], off offset:3072 nt
	s_or_b32 s0, s6, 6
	s_ashr_i32 s1, s0, 31
	s_lshl_b64 s[0:1], s[0:1], 12
	s_add_u32 s0, s36, s0
	s_addc_u32 s1, s37, s1
	s_or_b32 s4, s6, 7
	s_ashr_i32 s5, s4, 31
	s_waitcnt vmcnt(7)
	v_pk_mul_f32 v[44:45], v[78:79], v[78:79]
	v_pk_mul_f32 v[46:47], v[76:77], v[76:77]
	s_nop 0
	v_pk_mov_b32 v[56:57], v[46:47], v[44:45] op_sel:[1,0]
	v_mov_b32_e32 v47, v45
	v_pk_add_f32 v[44:45], v[56:57], v[46:47]
	s_waitcnt vmcnt(6)
	v_pk_mul_f32 v[46:47], v[70:71], v[70:71]
	v_pk_mul_f32 v[56:57], v[68:69], v[68:69]
	v_pk_add_f32 v[44:45], v[44:45], v[44:45] op_sel:[0,1] op_sel_hi:[1,0]
	v_pk_mov_b32 v[58:59], v[56:57], v[46:47] op_sel:[1,0]
	v_mov_b32_e32 v57, v47
	v_pk_add_f32 v[46:47], v[58:59], v[56:57]
	s_waitcnt vmcnt(5)
	v_mul_f32_e32 v56, v52, v52
	v_mul_f32_e32 v57, v53, v53
	v_pk_add_f32 v[46:47], v[46:47], v[46:47] op_sel:[0,1] op_sel_hi:[1,0]
	v_mov_b32_e32 v45, v56
	v_mov_b32_e32 v47, v57
	v_pk_add_f32 v[44:45], v[44:45], v[46:47]
	s_waitcnt vmcnt(4)
	v_mul_f32_e32 v46, v61, v61
	v_mul_f32_e32 v56, v63, v63
	v_mul_f32_e32 v58, v54, v54
	v_mul_f32_e32 v59, v55, v55
	v_pk_fma_f32 v[46:47], v[60:61], v[60:61], v[46:47] op_sel_hi:[1,1,0]
	v_pk_fma_f32 v[56:57], v[62:63], v[62:63], v[56:57] op_sel_hi:[1,1,0]
	v_mov_b32_e32 v47, v58
	v_mov_b32_e32 v57, v59
	v_pk_add_f32 v[46:47], v[46:47], v[56:57]
	s_nop 0
	v_pk_add_f32 v[44:45], v[44:45], v[46:47]
	s_nop 0
	v_add_f32_e32 v44, v44, v45
	s_waitcnt lgkmcnt(0)
	s_nop 4
	v_add_f32_dpp v44, v44, v44 quad_perm:[1,0,3,2] row_mask:0xf bank_mask:0xf
	s_waitcnt lgkmcnt(0)
	s_nop 4
	v_add_f32_dpp v44, v44, v44 quad_perm:[2,3,0,1] row_mask:0xf bank_mask:0xf
	ds_bpermute_b32 v45, v108, v44
	s_waitcnt lgkmcnt(0)
	v_add_f32_e32 v46, v44, v45
	v_lshl_add_u64 v[44:45], s[0:1], 0, v[88:89]
	global_load_dwordx4 v[84:87], v[44:45], off nt
	global_load_dwordx4 v[80:83], v[44:45], off offset:1024 nt
	ds_bpermute_b32 v47, v107, v46
	s_lshl_b64 s[0:1], s[4:5], 12
	s_add_u32 s0, s36, s0
	s_addc_u32 s1, s37, s1
	v_lshl_add_u64 v[92:93], s[0:1], 0, v[88:89]
	s_waitcnt lgkmcnt(0)
	v_add_f32_e32 v46, v46, v47
	ds_bpermute_b32 v47, v106, v46
	global_load_dwordx4 v[72:75], v[44:45], off offset:2048 nt
	global_load_dwordx4 v[64:67], v[44:45], off offset:3072 nt
	s_waitcnt lgkmcnt(0)
	v_add_f32_e32 v90, v46, v47
	ds_bpermute_b32 v91, v105, v90
	global_load_dwordx4 v[56:59], v[92:93], off nt
	global_load_dwordx4 v[44:47], v[92:93], off offset:1024 nt
	s_waitcnt lgkmcnt(0)
	v_add_f32_e32 v88, v90, v91
	v_fmamk_f32 v88, v88, 0x3a800000, v104
	v_mul_f32_e32 v89, 0x4f800000, v88
	v_cmp_gt_f32_e32 vcc, s3, v88
	s_waitcnt vmcnt(9)
	v_pk_mul_f32 v[90:91], v[48:49], v[48:49]
	s_waitcnt vmcnt(4)
	v_pk_mul_f32 v[116:117], v[80:81], v[80:81]
	v_cndmask_b32_e32 v114, v88, v89, vcc
	v_pk_mul_f32 v[88:89], v[50:51], v[50:51]
	v_sqrt_f32_e32 v115, v114
	v_pk_mov_b32 v[94:95], v[90:91], v[88:89] op_sel:[1,0]
	v_mov_b32_e32 v91, v89
	v_pk_add_f32 v[88:89], v[94:95], v[90:91]
	v_pk_mul_f32 v[90:91], v[42:43], v[42:43]
	v_pk_mul_f32 v[94:95], v[40:41], v[40:41]
	v_pk_add_f32 v[88:89], v[88:89], v[88:89] op_sel:[0,1] op_sel_hi:[1,0]
	v_pk_mov_b32 v[112:113], v[94:95], v[90:91] op_sel:[1,0]
	v_mov_b32_e32 v95, v91
	v_pk_add_f32 v[90:91], v[112:113], v[94:95]
	v_mul_f32_e32 v94, v32, v32
	v_mul_f32_e32 v95, v33, v33
	v_pk_add_f32 v[90:91], v[90:91], v[90:91] op_sel:[0,1] op_sel_hi:[1,0]
	v_mov_b32_e32 v89, v94
	v_mov_b32_e32 v91, v95
	v_pk_add_f32 v[88:89], v[88:89], v[90:91]
	v_mul_f32_e32 v90, v37, v37
	v_mul_f32_e32 v94, v39, v39
	v_mul_f32_e32 v112, v34, v34
	v_mul_f32_e32 v113, v35, v35
	v_pk_fma_f32 v[90:91], v[36:37], v[36:37], v[90:91] op_sel_hi:[1,1,0]
	v_pk_fma_f32 v[94:95], v[38:39], v[38:39], v[94:95] op_sel_hi:[1,1,0]
	v_mov_b32_e32 v91, v112
	v_mov_b32_e32 v95, v113
	v_pk_add_f32 v[90:91], v[90:91], v[94:95]
	s_nop 0
	v_pk_add_f32 v[88:89], v[88:89], v[90:91]
	v_add_u32_e32 v90, -1, v115
	v_add_f32_e32 v88, v88, v89
	v_fma_f32 v91, -v90, v115, v114
	v_cmp_ge_f32_e64 s[0:1], 0, v91
	v_add_u32_e32 v91, 1, v115
	v_fma_f32 v94, -v91, v115, v114
	s_waitcnt lgkmcnt(0)
	s_nop 4
	v_add_f32_dpp v88, v88, v88 quad_perm:[1,0,3,2] row_mask:0xf bank_mask:0xf
	v_cndmask_b32_e64 v90, v115, v90, s[0:1]
	v_cmp_lt_f32_e64 s[0:1], 0, v94
	s_waitcnt lgkmcnt(0)
	s_nop 4
	v_add_f32_dpp v88, v88, v88 quad_perm:[2,3,0,1] row_mask:0xf bank_mask:0xf
	ds_bpermute_b32 v89, v108, v88
	v_cndmask_b32_e64 v90, v90, v91, s[0:1]
	v_mul_f32_e32 v91, 0x37800000, v90
	v_cndmask_b32_e32 v90, v90, v91, vcc
	v_cmp_class_f32_e32 vcc, v114, v111
	s_waitcnt lgkmcnt(0)
	v_add_f32_e32 v94, v88, v89
	ds_bpermute_b32 v95, v107, v94
	v_cndmask_b32_e32 v120, v90, v114, vcc
	v_div_scale_f32 v121, s[0:1], v120, v120, 1.0
	v_rcp_f32_e32 v122, v121
	s_waitcnt lgkmcnt(0)
	v_add_f32_e32 v94, v94, v95
	ds_bpermute_b32 v95, v106, v94
	global_load_dwordx4 v[88:91], v[92:93], off offset:3072 nt
	v_fma_f32 v112, -v121, v122, 1.0
	v_fmac_f32_e32 v122, v112, v122
	v_pk_mul_f32 v[112:113], v[84:85], v[84:85]
	s_waitcnt lgkmcnt(0)
	v_add_f32_e32 v124, v94, v95
	v_pk_mul_f32 v[94:95], v[86:87], v[86:87]
	ds_bpermute_b32 v125, v105, v124
	v_pk_mov_b32 v[114:115], v[112:113], v[94:95] op_sel:[1,0]
	v_mov_b32_e32 v113, v95
	global_load_dwordx4 v[92:95], v[92:93], off offset:2048 nt
	v_pk_add_f32 v[112:113], v[114:115], v[112:113]
	v_pk_mul_f32 v[114:115], v[82:83], v[82:83]
	v_pk_add_f32 v[112:113], v[112:113], v[112:113] op_sel:[0,1] op_sel_hi:[1,0]
	v_pk_mov_b32 v[118:119], v[116:117], v[114:115] op_sel:[1,0]
	s_waitcnt lgkmcnt(0)
	v_add_f32_e32 v114, v124, v125
	v_fmamk_f32 v114, v114, 0x3a800000, v104
	v_mov_b32_e32 v117, v115
	v_mul_f32_e32 v115, 0x4f800000, v114
	v_cmp_gt_f32_e64 s[0:1], s3, v114
	v_div_scale_f32 v123, vcc, 1.0, v120, 1.0
	s_nop 0
	v_cndmask_b32_e64 v124, v114, v115, s[0:1]
	v_pk_add_f32 v[114:115], v[118:119], v[116:117]
	s_waitcnt vmcnt(4)
	v_mul_f32_e32 v116, v64, v64
	v_mul_f32_e32 v117, v65, v65
	v_pk_add_f32 v[114:115], v[114:115], v[114:115] op_sel:[0,1] op_sel_hi:[1,0]
	v_mov_b32_e32 v113, v116
	v_mov_b32_e32 v115, v117
	v_pk_add_f32 v[112:113], v[112:113], v[114:115]
	v_mul_f32_e32 v114, v73, v73
	v_mul_f32_e32 v116, v75, v75
	v_mul_f32_e32 v118, v66, v66
	v_mul_f32_e32 v119, v67, v67
	v_pk_fma_f32 v[114:115], v[72:73], v[72:73], v[114:115] op_sel_hi:[1,1,0]
	v_pk_fma_f32 v[116:117], v[74:75], v[74:75], v[116:117] op_sel_hi:[1,1,0]
	v_mov_b32_e32 v115, v118
	v_mov_b32_e32 v117, v119
	v_pk_add_f32 v[114:115], v[114:115], v[116:117]
	v_sqrt_f32_e32 v118, v124
	v_pk_add_f32 v[112:113], v[112:113], v[114:115]
	v_mul_f32_e32 v126, v123, v122
	v_add_f32_e32 v112, v112, v113
	v_add_u32_e32 v115, -1, v118
	v_fma_f32 v116, -v115, v118, v124
	v_cmp_ge_f32_e64 s[4:5], 0, v116
	v_add_u32_e32 v116, 1, v118
	s_waitcnt lgkmcnt(0)
	s_nop 4
	v_add_f32_dpp v112, v112, v112 quad_perm:[1,0,3,2] row_mask:0xf bank_mask:0xf
	v_fma_f32 v117, -v116, v118, v124
	v_cndmask_b32_e64 v115, v118, v115, s[4:5]
	v_cmp_lt_f32_e64 s[4:5], 0, v117
	v_fma_f32 v127, -v121, v126, v123
	s_waitcnt lgkmcnt(0)
	s_nop 4
	v_add_f32_dpp v112, v112, v112 quad_perm:[2,3,0,1] row_mask:0xf bank_mask:0xf
	ds_bpermute_b32 v113, v108, v112
	v_cndmask_b32_e64 v115, v115, v116, s[4:5]
	v_mul_f32_e32 v116, 0x37800000, v115
	v_fmac_f32_e32 v126, v127, v122
	v_cndmask_b32_e64 v115, v115, v116, s[0:1]
	s_waitcnt lgkmcnt(0)
	v_add_f32_e32 v112, v112, v113
	ds_bpermute_b32 v113, v107, v112
	v_cmp_class_f32_e64 s[0:1], v124, v111
	v_fma_f32 v114, -v121, v126, v123
	v_div_fmas_f32 v122, v114, v122, v126
	v_cndmask_b32_e64 v121, v115, v124, s[0:1]
	v_div_scale_f32 v123, s[0:1], v121, v121, 1.0
	s_waitcnt lgkmcnt(0)
	v_add_f32_e32 v112, v112, v113
	v_rcp_f32_e32 v124, v123
	ds_bpermute_b32 v113, v106, v112
	v_fma_f32 v114, -v123, v124, 1.0
	v_fmac_f32_e32 v124, v114, v124
	s_waitcnt lgkmcnt(0)
	v_add_f32_e32 v125, v112, v113
	s_waitcnt vmcnt(3)
	v_pk_mul_f32 v[112:113], v[58:59], v[58:59]
	v_pk_mul_f32 v[114:115], v[56:57], v[56:57]
	s_nop 0
	v_pk_mov_b32 v[116:117], v[114:115], v[112:113] op_sel:[1,0]
	v_mov_b32_e32 v115, v113
	v_pk_add_f32 v[112:113], v[116:117], v[114:115]
	s_waitcnt vmcnt(2)
	v_pk_mul_f32 v[114:115], v[46:47], v[46:47]
	v_pk_mul_f32 v[116:117], v[44:45], v[44:45]
	v_pk_add_f32 v[112:113], v[112:113], v[112:113] op_sel:[0,1] op_sel_hi:[1,0]
	v_pk_mov_b32 v[118:119], v[116:117], v[114:115] op_sel:[1,0]
	v_mov_b32_e32 v117, v115
	v_pk_add_f32 v[114:115], v[118:119], v[116:117]
	s_waitcnt vmcnt(1)
	v_mul_f32_e32 v116, v88, v88
	v_mul_f32_e32 v117, v89, v89
	v_pk_add_f32 v[114:115], v[114:115], v[114:115] op_sel:[0,1] op_sel_hi:[1,0]
	v_mov_b32_e32 v113, v116
	v_mov_b32_e32 v115, v117
	v_pk_add_f32 v[112:113], v[112:113], v[114:115]
	s_waitcnt vmcnt(0)
	v_mul_f32_e32 v114, v93, v93
	v_mul_f32_e32 v116, v90, v90
	v_pk_fma_f32 v[114:115], v[92:93], v[92:93], v[114:115] op_sel_hi:[1,1,0]
	v_div_fixup_f32 v118, v122, v120, 1.0
	v_mov_b32_e32 v115, v116
	v_mul_f32_e32 v116, v95, v95
	v_pk_fma_f32 v[116:117], v[94:95], v[94:95], v[116:117] op_sel_hi:[1,1,0]
	s_nop 0
	v_mul_f32_e32 v117, v91, v91
	v_pk_add_f32 v[114:115], v[114:115], v[116:117]
	ds_bpermute_b32 v116, v105, v125
	v_pk_add_f32 v[112:113], v[112:113], v[114:115]
	v_div_scale_f32 v117, vcc, 1.0, v121, 1.0
	v_add_f32_e32 v112, v112, v113
	s_waitcnt lgkmcnt(0)
	v_add_f32_e32 v116, v125, v116
	v_fmamk_f32 v116, v116, 0x3a800000, v104
	v_mul_f32_e32 v119, 0x4f800000, v116
	v_cmp_gt_f32_e64 s[0:1], s3, v116
	s_waitcnt lgkmcnt(0)
	s_nop 4
	v_add_f32_dpp v110, v112, v112 quad_perm:[1,0,3,2] row_mask:0xf bank_mask:0xf
	v_cndmask_b32_e64 v116, v116, v119, s[0:1]
	v_sqrt_f32_e32 v119, v116
	v_mul_f32_e32 v114, v117, v124
	v_fma_f32 v115, -v123, v114, v117
	s_waitcnt lgkmcnt(0)
	s_nop 4
	v_add_f32_dpp v109, v110, v110 quad_perm:[2,3,0,1] row_mask:0xf bank_mask:0xf
	ds_bpermute_b32 v108, v108, v109
	v_fmac_f32_e32 v114, v115, v124
	v_add_u32_e32 v115, -1, v119
	v_fma_f32 v113, -v123, v114, v117
	v_fma_f32 v117, -v115, v119, v116
	s_waitcnt lgkmcnt(0)
	v_add_f32_e32 v108, v109, v108
	ds_bpermute_b32 v107, v107, v108
	v_cmp_ge_f32_e64 s[4:5], 0, v117
	v_pk_mul_f32 v[76:77], v[76:77], v[118:119] op_sel_hi:[1,0]
	v_pk_mul_f32 v[78:79], v[78:79], v[118:119] op_sel_hi:[1,0]
	v_cndmask_b32_e64 v112, v119, v115, s[4:5]
	s_waitcnt lgkmcnt(0)
	v_add_f32_e32 v107, v108, v107
	ds_bpermute_b32 v108, v106, v107
	v_add_u32_e32 v115, 1, v119
	v_fma_f32 v117, -v115, v119, v116
	v_cmp_lt_f32_e64 s[4:5], 0, v117
	v_div_fmas_f32 v106, v113, v124, v114
	s_waitcnt lgkmcnt(0)
	v_add_f32_e32 v107, v107, v108
	v_cndmask_b32_e64 v110, v112, v115, s[4:5]
	v_mul_f32_e32 v112, 0x37800000, v110
	ds_bpermute_b32 v105, v105, v107
	v_cndmask_b32_e64 v110, v110, v112, s[0:1]
	v_cmp_class_f32_e64 s[0:1], v116, v111
	v_div_fixup_f32 v106, v106, v121, 1.0
	v_pk_mul_f32 v[68:69], v[68:69], v[118:119] op_sel_hi:[1,0]
	v_cndmask_b32_e64 v109, v110, v116, s[0:1]
	v_div_scale_f32 v110, s[0:1], v109, v109, 1.0
	v_rcp_f32_e32 v112, v110
	s_waitcnt lgkmcnt(0)
	v_add_f32_e32 v105, v107, v105
	v_fmac_f32_e32 v104, 0x3a800000, v105
	v_mul_f32_e32 v105, 0x4f800000, v104
	v_cmp_gt_f32_e64 s[0:1], s3, v104
	v_fma_f32 v113, -v110, v112, 1.0
	v_fmac_f32_e32 v112, v113, v112
	v_cndmask_b32_e64 v104, v104, v105, s[0:1]
	v_div_scale_f32 v108, vcc, 1.0, v109, 1.0
	v_sqrt_f32_e32 v105, v104
	v_mul_f32_e32 v113, v108, v112
	v_fma_f32 v107, -v110, v113, v108
	v_fmac_f32_e32 v113, v107, v112
	v_fma_f32 v107, -v110, v113, v108
	v_add_u32_e32 v108, -1, v105
	v_fma_f32 v110, -v108, v105, v104
	v_cmp_ge_f32_e64 s[4:5], 0, v110
	v_add_u32_e32 v110, 1, v105
	v_pk_mul_f32 v[70:71], v[70:71], v[118:119] op_sel_hi:[1,0]
	v_cndmask_b32_e64 v108, v105, v108, s[4:5]
	v_fma_f32 v105, -v110, v105, v104
	v_cmp_lt_f32_e64 s[4:5], 0, v105
	v_pk_mul_f32 v[60:61], v[60:61], v[118:119] op_sel_hi:[1,0]
	v_pk_mul_f32 v[62:63], v[62:63], v[118:119] op_sel_hi:[1,0]
	v_cndmask_b32_e64 v105, v108, v110, s[4:5]
	v_mul_f32_e32 v108, 0x37800000, v105
	v_cndmask_b32_e64 v105, v105, v108, s[0:1]
	v_cmp_class_f32_e64 s[0:1], v104, v111
	v_pk_mul_f32 v[52:53], v[52:53], v[118:119] op_sel_hi:[1,0]
	v_pk_mul_f32 v[54:55], v[54:55], v[118:119] op_sel_hi:[1,0]
	v_cndmask_b32_e64 v105, v105, v104, s[0:1]
	v_div_scale_f32 v108, s[0:1], v105, v105, 1.0
	v_rcp_f32_e32 v110, v108
	v_div_fmas_f32 v104, v107, v112, v113
	v_div_fixup_f32 v104, v104, v109, 1.0
	v_pk_fma_f32 v[78:79], v[2:3], v[78:79], v[6:7]
	v_fma_f32 v107, -v108, v110, 1.0
	v_fmac_f32_e32 v110, v107, v110
	v_div_scale_f32 v107, vcc, 1.0, v105, 1.0
	v_mul_f32_e32 v109, v107, v110
	v_fma_f32 v111, -v108, v109, v107
	v_fmac_f32_e32 v109, v111, v110
	v_fma_f32 v107, -v108, v109, v107
	v_div_fmas_f32 v107, v107, v110, v109
	v_pk_mul_f32 v[48:49], v[48:49], v[106:107] op_sel_hi:[1,0]
	v_pk_mul_f32 v[50:51], v[50:51], v[106:107] op_sel_hi:[1,0]
	v_pk_mul_f32 v[40:41], v[40:41], v[106:107] op_sel_hi:[1,0]
	v_pk_mul_f32 v[42:43], v[42:43], v[106:107] op_sel_hi:[1,0]
	v_pk_mul_f32 v[36:37], v[36:37], v[106:107] op_sel_hi:[1,0]
	v_pk_mul_f32 v[38:39], v[38:39], v[106:107] op_sel_hi:[1,0]
	v_pk_mul_f32 v[32:33], v[32:33], v[106:107] op_sel_hi:[1,0]
	v_pk_mul_f32 v[34:35], v[34:35], v[106:107] op_sel_hi:[1,0]
	v_pk_fma_f32 v[76:77], v[0:1], v[76:77], v[4:5]
	v_pk_fma_f32 v[70:71], v[10:11], v[70:71], v[14:15]
	v_pk_fma_f32 v[68:69], v[8:9], v[68:69], v[12:13]
	v_pk_fma_f32 v[62:63], v[18:19], v[62:63], v[22:23]
	v_pk_fma_f32 v[60:61], v[16:17], v[60:61], v[20:21]
	v_pk_fma_f32 v[54:55], v[26:27], v[54:55], v[30:31]
	v_pk_fma_f32 v[52:53], v[24:25], v[52:53], v[28:29]
	v_pk_fma_f32 v[50:51], v[2:3], v[50:51], v[6:7]
	v_pk_fma_f32 v[48:49], v[0:1], v[48:49], v[4:5]
	v_pk_fma_f32 v[42:43], v[10:11], v[42:43], v[14:15]
	v_pk_fma_f32 v[40:41], v[8:9], v[40:41], v[12:13]
	v_pk_fma_f32 v[38:39], v[18:19], v[38:39], v[22:23]
	v_pk_fma_f32 v[36:37], v[16:17], v[36:37], v[20:21]
	v_pk_fma_f32 v[34:35], v[26:27], v[34:35], v[30:31]
	v_pk_fma_f32 v[32:33], v[24:25], v[32:33], v[28:29]
	v_cvt_pk_bf16_f32 v76, v76, v77
	v_cvt_pk_bf16_f32 v77, v78, v79
	v_cvt_pk_bf16_f32 v68, v68, v69
	v_cvt_pk_bf16_f32 v69, v70, v71
	v_cvt_pk_bf16_f32 v60, v60, v61
	v_cvt_pk_bf16_f32 v61, v62, v63
	v_cvt_pk_bf16_f32 v52, v52, v53
	v_cvt_pk_bf16_f32 v53, v54, v55
	v_cvt_pk_bf16_f32 v48, v48, v49
	v_cvt_pk_bf16_f32 v49, v50, v51
	v_cvt_pk_bf16_f32 v40, v40, v41
	v_cvt_pk_bf16_f32 v41, v42, v43
	v_cvt_pk_bf16_f32 v36, v36, v37
	v_cvt_pk_bf16_f32 v37, v38, v39
	v_cvt_pk_bf16_f32 v32, v32, v33
	v_cvt_pk_bf16_f32 v33, v34, v35
	global_store_dwordx2 v[96:97], v[76:77], off offset:512
	global_store_dwordx2 v[98:99], v[68:69], off offset:512
	global_store_dwordx2 v[100:101], v[60:61], off offset:512
	global_store_dwordx2 v[102:103], v[52:53], off offset:512
	global_store_dwordx2 v[96:97], v[48:49], off offset:640
	global_store_dwordx2 v[98:99], v[40:41], off offset:640
	global_store_dwordx2 v[100:101], v[36:37], off offset:640
	global_store_dwordx2 v[102:103], v[32:33], off offset:640
	v_pk_mul_f32 v[32:33], v[84:85], v[104:105] op_sel_hi:[1,0]
	v_pk_mul_f32 v[34:35], v[86:87], v[104:105] op_sel_hi:[1,0]
	v_pk_fma_f32 v[32:33], v[0:1], v[32:33], v[4:5]
	v_pk_fma_f32 v[34:35], v[2:3], v[34:35], v[6:7]
	v_cvt_pk_bf16_f32 v32, v32, v33
	v_cvt_pk_bf16_f32 v33, v34, v35
	global_store_dwordx2 v[96:97], v[32:33], off offset:768
	v_pk_mul_f32 v[32:33], v[80:81], v[104:105] op_sel_hi:[1,0]
	v_pk_mul_f32 v[34:35], v[82:83], v[104:105] op_sel_hi:[1,0]
	v_pk_fma_f32 v[32:33], v[8:9], v[32:33], v[12:13]
	v_pk_fma_f32 v[34:35], v[10:11], v[34:35], v[14:15]
	v_cvt_pk_bf16_f32 v32, v32, v33
	v_cvt_pk_bf16_f32 v33, v34, v35
	global_store_dwordx2 v[98:99], v[32:33], off offset:768
	v_pk_mul_f32 v[32:33], v[72:73], v[104:105] op_sel_hi:[1,0]
	v_pk_mul_f32 v[34:35], v[74:75], v[104:105] op_sel_hi:[1,0]
	v_pk_fma_f32 v[32:33], v[16:17], v[32:33], v[20:21]
	v_pk_fma_f32 v[34:35], v[18:19], v[34:35], v[22:23]
	v_cvt_pk_bf16_f32 v32, v32, v33
	v_cvt_pk_bf16_f32 v33, v34, v35
	global_store_dwordx2 v[100:101], v[32:33], off offset:768
	v_pk_mul_f32 v[32:33], v[64:65], v[104:105] op_sel_hi:[1,0]
	v_pk_mul_f32 v[34:35], v[66:67], v[104:105] op_sel_hi:[1,0]
	v_pk_fma_f32 v[32:33], v[24:25], v[32:33], v[28:29]
	v_pk_fma_f32 v[34:35], v[26:27], v[34:35], v[30:31]
	v_div_fixup_f32 v108, v107, v105, 1.0
	v_cvt_pk_bf16_f32 v32, v32, v33
	v_cvt_pk_bf16_f32 v33, v34, v35
	global_store_dwordx2 v[102:103], v[32:33], off offset:768
	v_pk_mul_f32 v[32:33], v[56:57], v[108:109] op_sel_hi:[1,0]
	v_pk_mul_f32 v[34:35], v[58:59], v[108:109] op_sel_hi:[1,0]
	v_pk_fma_f32 v[0:1], v[0:1], v[32:33], v[4:5]
	v_pk_fma_f32 v[2:3], v[2:3], v[34:35], v[6:7]
	v_cvt_pk_bf16_f32 v0, v0, v1
	v_cvt_pk_bf16_f32 v1, v2, v3
	global_store_dwordx2 v[96:97], v[0:1], off offset:896
	v_pk_mul_f32 v[0:1], v[44:45], v[108:109] op_sel_hi:[1,0]
	v_pk_mul_f32 v[2:3], v[46:47], v[108:109] op_sel_hi:[1,0]
	v_pk_fma_f32 v[0:1], v[8:9], v[0:1], v[12:13]
	v_pk_fma_f32 v[2:3], v[10:11], v[2:3], v[14:15]
	v_cvt_pk_bf16_f32 v0, v0, v1
	v_cvt_pk_bf16_f32 v1, v2, v3
	global_store_dwordx2 v[98:99], v[0:1], off offset:896
	v_pk_mul_f32 v[0:1], v[92:93], v[108:109] op_sel_hi:[1,0]
	v_pk_mul_f32 v[2:3], v[94:95], v[108:109] op_sel_hi:[1,0]
	v_pk_fma_f32 v[0:1], v[16:17], v[0:1], v[20:21]
	v_pk_fma_f32 v[2:3], v[18:19], v[2:3], v[22:23]
	v_cvt_pk_bf16_f32 v0, v0, v1
	v_cvt_pk_bf16_f32 v1, v2, v3
	global_store_dwordx2 v[100:101], v[0:1], off offset:896
	v_pk_mul_f32 v[0:1], v[88:89], v[108:109] op_sel_hi:[1,0]
	v_pk_mul_f32 v[2:3], v[90:91], v[108:109] op_sel_hi:[1,0]
	v_pk_fma_f32 v[0:1], v[24:25], v[0:1], v[28:29]
	v_pk_fma_f32 v[2:3], v[26:27], v[2:3], v[30:31]
	v_cvt_pk_bf16_f32 v0, v0, v1
	v_cvt_pk_bf16_f32 v1, v2, v3
	global_store_dwordx2 v[102:103], v[0:1], off offset:896
